# v82 + nt on the P10 AFFN epilogue stores (streaming output should not evict A/B operands from L2)
# speedup vs baseline: 1.0095x; 1.0014x over previous
.LBB0_1297:
	s_lshr_b32 s17, s4, 5
	s_mul_i32 s20, s17, 0x1600
	s_ashr_i32 s21, s20, 31
	s_lshl_b64 s[20:21], s[20:21], 2
	s_add_u32 s17, s46, s20
	s_addc_u32 s19, s47, s21
	s_lshl_b32 s20, s52, 8
	s_ashr_i32 s21, s20, 31
	s_lshl_b64 s[20:21], s[20:21], 2
	s_add_u32 s17, s17, s20
	s_addc_u32 s19, s19, s21
	s_lshl_b32 s20, s54, 2
	v_lshl_add_u32 v166, s4, 8, v1
	s_add_u32 s20, s17, s20
	v_ashrrev_i32_e32 v167, 31, v166
	s_addc_u32 s21, s19, 0
	v_lshlrev_b32_e32 v78, 2, v156
	v_lshl_add_u64 v[174:175], v[166:167], 2, s[10:11]
	v_add_u32_e32 v174, 0x80, v166
	v_ashrrev_i32_e32 v175, 31, v174
	v_lshl_add_u64 v[178:179], v[174:175], 2, s[10:11]
	s_lshl_b32 s20, s52, 7
	s_ashr_i32 s21, s20, 31
	s_lshl_b64 s[20:21], s[20:21], 1
	s_lshl_b32 s4, s54, 1
	s_andn2_b64 vcc, exec, s[40:41]
	s_waitcnt vmcnt(0)
	v_mov_b64_e32 v[94:95], v[234:235]
	v_mov_b64_e32 v[96:97], v[236:237]
	v_mov_b64_e32 v[82:83], v[238:239]
	v_mov_b64_e32 v[84:85], v[240:241]
	v_mov_b64_e32 v[78:79], v[242:243]
	v_mov_b64_e32 v[80:81], v[244:245]
	v_mov_b64_e32 v[70:71], v[246:247]
	v_mov_b64_e32 v[72:73], v[248:249]
	v_mov_b32_e32 v154, v250
	v_mov_b32_e32 v167, v251
	v_mov_b32_e32 v168, v252
	v_mov_b32_e32 v170, v253
	v_mov_b32_e32 v172, v254
	v_mov_b32_e32 v175, v233
	v_mov_b32_e32 v181, v232
	v_mov_b32_e32 v179, v177
	v_mov_b32_e32 v177, 0x358637bd
	v_fmamk_f32 v154, v154, 0x3a800000, v177
	v_fmamk_f32 v167, v167, 0x3a800000, v177
	v_rsq_f32_e32 v182, v167
	v_fmamk_f32 v167, v168, 0x3a800000, v177
	v_rsq_f32_e32 v154, v154
	v_rsq_f32_e32 v180, v167
	v_fmamk_f32 v167, v170, 0x3a800000, v177
	v_rsq_f32_e32 v178, v167
	v_fmamk_f32 v167, v172, 0x3a800000, v177
	v_rsq_f32_e32 v176, v167
	v_fmamk_f32 v167, v175, 0x3a800000, v177
	v_rsq_f32_e32 v172, v167
	v_fmamk_f32 v167, v181, 0x3a800000, v177
	v_rsq_f32_e32 v170, v167
	v_fmamk_f32 v167, v179, 0x3a800000, v177
	s_lshr_b32 s98, s18, 5
	s_mul_i32 s98, s98, 0x1600
	s_lshl_b32 s99, s16, 8
	s_add_i32 s98, s98, s99
	s_add_i32 s98, s98, s54
	s_lshl_b32 s98, s98, 2
	s_add_u32 s98, s46, s98
	s_addc_u32 s99, s47, 0
	v_lshlrev_b32_e32 v233, 2, v156
	v_lshl_add_u32 v232, s18, 8, v1
	global_load_dwordx4 v[234:237], v233, s[98:99]
	global_load_dwordx4 v[238:241], v233, s[98:99] offset:16
	global_load_dwordx4 v[242:245], v233, s[98:99] offset:512
	global_load_dwordx4 v[246:249], v233, s[98:99] offset:528
	v_lshlrev_b32_e32 v232, 2, v232
	global_load_dword v250, v232, s[10:11]
	global_load_dword v251, v232, s[10:11] offset:64
	global_load_dword v252, v232, s[10:11] offset:128
	global_load_dword v253, v232, s[10:11] offset:192
	global_load_dword v254, v232, s[10:11] offset:512
	global_load_dword v233, v232, s[10:11] offset:576
	global_load_dword v177, v232, s[10:11] offset:704
	global_load_dword v232, v232, s[10:11] offset:640
	v_pk_fma_f32 v[142:143], v[142:143], v[154:155], v[94:95] op_sel_hi:[1,0,1]
	v_rsq_f32_e32 v168, v167
	v_mul_f32_e32 v167, 0xbfb8aa3b, v142
	v_exp_f32_e32 v167, v167
	v_pk_fma_f32 v[138:139], v[138:139], v[154:155], v[82:83] op_sel_hi:[1,0,1]
	v_pk_fma_f32 v[134:135], v[134:135], v[154:155], v[78:79] op_sel_hi:[1,0,1]
	v_pk_fma_f32 v[140:141], v[140:141], v[154:155], v[84:85] op_sel_hi:[1,0,1]
	v_add_f32_e32 v167, 1.0, v167
	v_rcp_f32_e32 v184, v167
	v_mul_f32_e32 v167, 0xbfb8aa3b, v138
	v_exp_f32_e32 v167, v167
	v_pk_fma_f32 v[130:131], v[130:131], v[154:155], v[70:71] op_sel_hi:[1,0,1]
	v_pk_fma_f32 v[144:145], v[144:145], v[154:155], v[96:97] op_sel_hi:[1,0,1]
	v_pk_fma_f32 v[136:137], v[136:137], v[154:155], v[80:81] op_sel_hi:[1,0,1]
	v_add_f32_e32 v167, 1.0, v167
	v_rcp_f32_e32 v186, v167
	v_mul_f32_e32 v167, 0xbfb8aa3b, v143
	v_exp_f32_e32 v167, v167
	v_pk_fma_f32 v[132:133], v[132:133], v[154:155], v[72:73] op_sel_hi:[1,0,1]
	v_lshlrev_b32_e32 v154, 1, v156
	v_pk_fma_f32 v[122:123], v[122:123], v[182:183], v[82:83] op_sel_hi:[1,0,1]
	v_add_f32_e32 v167, 1.0, v167
	v_rcp_f32_e32 v185, v167
	v_pk_fma_f32 v[126:127], v[126:127], v[182:183], v[94:95] op_sel_hi:[1,0,1]
	v_pk_fma_f32 v[118:119], v[118:119], v[182:183], v[78:79] op_sel_hi:[1,0,1]
	v_pk_fma_f32 v[124:125], v[124:125], v[182:183], v[84:85] op_sel_hi:[1,0,1]
	v_pk_mul_f32 v[142:143], v[142:143], v[184:185]
	v_pk_fma_f32 v[106:107], v[106:107], v[182:183], v[70:71] op_sel_hi:[1,0,1]
	v_pk_mul_f32 v[134:135], v[134:135], v[142:143]
	v_mul_f32_e32 v142, 0xbfb8aa3b, v139
	v_exp_f32_e32 v142, v142
	v_pk_fma_f32 v[128:129], v[128:129], v[182:183], v[96:97] op_sel_hi:[1,0,1]
	v_pk_fma_f32 v[120:121], v[120:121], v[182:183], v[80:81] op_sel_hi:[1,0,1]
	v_pk_fma_f32 v[108:109], v[108:109], v[182:183], v[72:73] op_sel_hi:[1,0,1]
	v_add_f32_e32 v142, 1.0, v142
	v_rcp_f32_e32 v187, v142
	v_pk_fma_f32 v[110:111], v[110:111], v[180:181], v[82:83] op_sel_hi:[1,0,1]
	v_pk_fma_f32 v[102:103], v[102:103], v[180:181], v[78:79] op_sel_hi:[1,0,1]
	v_pk_fma_f32 v[112:113], v[112:113], v[180:181], v[84:85] op_sel_hi:[1,0,1]
	v_pk_mul_f32 v[138:139], v[138:139], v[186:187]
	v_pk_fma_f32 v[86:87], v[86:87], v[180:181], v[70:71] op_sel_hi:[1,0,1]
	v_pk_mul_f32 v[138:139], v[130:131], v[138:139]
	v_mul_f32_e32 v131, 0xbfb8aa3b, v140
	v_exp_f32_e32 v131, v131
	v_mul_f32_e32 v130, 0xbfb8aa3b, v144
	v_exp_f32_e32 v130, v130
	v_pk_fma_f32 v[104:105], v[104:105], v[180:181], v[80:81] op_sel_hi:[1,0,1]
	v_add_f32_e32 v131, 1.0, v131
	v_rcp_f32_e32 v142, v131
	v_mul_f32_e32 v131, 0xbfb8aa3b, v145
	v_exp_f32_e32 v131, v131
	v_add_f32_e32 v130, 1.0, v130
	v_rcp_f32_e32 v130, v130
	v_pk_fma_f32 v[88:89], v[88:89], v[180:181], v[72:73] op_sel_hi:[1,0,1]
	v_add_f32_e32 v131, 1.0, v131
	v_rcp_f32_e32 v131, v131
	v_pk_fma_f32 v[90:91], v[90:91], v[178:179], v[82:83] op_sel_hi:[1,0,1]
	v_pk_fma_f32 v[74:75], v[74:75], v[178:179], v[78:79] op_sel_hi:[1,0,1]
	v_pk_fma_f32 v[92:93], v[92:93], v[178:179], v[84:85] op_sel_hi:[1,0,1]
	v_pk_mul_f32 v[130:131], v[144:145], v[130:131]
	v_pk_fma_f32 v[66:67], v[66:67], v[178:179], v[70:71] op_sel_hi:[1,0,1]
	v_pk_mul_f32 v[136:137], v[136:137], v[130:131]
	v_mul_f32_e32 v130, 0xbfb8aa3b, v141
	v_exp_f32_e32 v130, v130
	v_pk_fma_f32 v[76:77], v[76:77], v[178:179], v[80:81] op_sel_hi:[1,0,1]
	v_pk_fma_f32 v[68:69], v[68:69], v[178:179], v[72:73] op_sel_hi:[1,0,1]
	v_pk_fma_f32 v[58:59], v[58:59], v[176:177], v[82:83] op_sel_hi:[1,0,1]
	v_add_f32_e32 v130, 1.0, v130
	v_rcp_f32_e32 v143, v130
	v_pk_fma_f32 v[62:63], v[62:63], v[176:177], v[94:95] op_sel_hi:[1,0,1]
	v_pk_fma_f32 v[54:55], v[54:55], v[176:177], v[78:79] op_sel_hi:[1,0,1]
	v_pk_fma_f32 v[60:61], v[60:61], v[176:177], v[84:85] op_sel_hi:[1,0,1]
	v_pk_mul_f32 v[130:131], v[140:141], v[142:143]
	v_pk_fma_f32 v[42:43], v[42:43], v[176:177], v[70:71] op_sel_hi:[1,0,1]
	v_pk_mul_f32 v[140:141], v[132:133], v[130:131]
	v_cvt_pk_bf16_f32 v130, v134, v135
	v_mov_b64_e32 v[134:135], s[8:9]
	v_cvt_pk_bf16_f32 v131, v136, v137
	v_mad_i64_i32 v[136:137], s[22:23], v166, s92, v[134:135]
	v_lshl_add_u64 v[136:137], v[136:137], 0, s[20:21]
	v_lshl_add_u64 v[136:137], v[136:137], 0, s[4:5]
	v_cvt_pk_bf16_f32 v132, v138, v139
	v_cvt_pk_bf16_f32 v133, v140, v141
	v_lshl_add_u64 v[136:137], v[136:137], 0, v[154:155]
	global_store_dwordx4 v[136:137], v[130:133], off nt
	v_pk_fma_f32 v[64:65], v[64:65], v[176:177], v[96:97] op_sel_hi:[1,0,1]
	v_pk_fma_f32 v[56:57], v[56:57], v[176:177], v[80:81] op_sel_hi:[1,0,1]
	v_mul_f32_e32 v131, 0xbfb8aa3b, v122
	v_exp_f32_e32 v131, v131
	v_mul_f32_e32 v130, 0xbfb8aa3b, v126
	v_exp_f32_e32 v130, v130
	v_pk_fma_f32 v[44:45], v[44:45], v[176:177], v[72:73] op_sel_hi:[1,0,1]
	v_add_f32_e32 v131, 1.0, v131
	v_rcp_f32_e32 v132, v131
	v_mul_f32_e32 v131, 0xbfb8aa3b, v127
	v_exp_f32_e32 v131, v131
	v_add_f32_e32 v130, 1.0, v130
	v_rcp_f32_e32 v130, v130
	v_pk_fma_f32 v[46:47], v[46:47], v[172:173], v[82:83] op_sel_hi:[1,0,1]
	v_add_f32_e32 v131, 1.0, v131
	v_rcp_f32_e32 v131, v131
	v_pk_fma_f32 v[38:39], v[38:39], v[172:173], v[78:79] op_sel_hi:[1,0,1]
	v_pk_fma_f32 v[48:49], v[48:49], v[172:173], v[84:85] op_sel_hi:[1,0,1]
	v_pk_fma_f32 v[26:27], v[26:27], v[172:173], v[70:71] op_sel_hi:[1,0,1]
	v_pk_mul_f32 v[126:127], v[126:127], v[130:131]
	v_pk_fma_f32 v[40:41], v[40:41], v[172:173], v[80:81] op_sel_hi:[1,0,1]
	v_pk_mul_f32 v[118:119], v[118:119], v[126:127]
	v_mul_f32_e32 v126, 0xbfb8aa3b, v123
	v_exp_f32_e32 v126, v126
	v_pk_fma_f32 v[28:29], v[28:29], v[172:173], v[72:73] op_sel_hi:[1,0,1]
	v_pk_fma_f32 v[30:31], v[30:31], v[170:171], v[82:83] op_sel_hi:[1,0,1]
	v_pk_fma_f32 v[22:23], v[22:23], v[170:171], v[78:79] op_sel_hi:[1,0,1]
	v_add_f32_e32 v126, 1.0, v126
	v_rcp_f32_e32 v133, v126
	v_pk_fma_f32 v[32:33], v[32:33], v[170:171], v[84:85] op_sel_hi:[1,0,1]
	v_pk_fma_f32 v[10:11], v[10:11], v[170:171], v[70:71] op_sel_hi:[1,0,1]
	v_pk_fma_f32 v[24:25], v[24:25], v[170:171], v[80:81] op_sel_hi:[1,0,1]
	v_pk_mul_f32 v[122:123], v[122:123], v[132:133]
	v_pk_fma_f32 v[12:13], v[12:13], v[170:171], v[72:73] op_sel_hi:[1,0,1]
	v_pk_mul_f32 v[122:123], v[106:107], v[122:123]
	v_mul_f32_e32 v107, 0xbfb8aa3b, v124
	v_exp_f32_e32 v107, v107
	v_mul_f32_e32 v106, 0xbfb8aa3b, v128
	v_exp_f32_e32 v106, v106
	v_pk_fma_f32 v[14:15], v[14:15], v[168:169], v[82:83] op_sel_hi:[1,0,1]
	v_add_f32_e32 v107, 1.0, v107
	v_rcp_f32_e32 v126, v107
	v_mul_f32_e32 v107, 0xbfb8aa3b, v129
	v_exp_f32_e32 v107, v107
	v_add_f32_e32 v106, 1.0, v106
	v_rcp_f32_e32 v106, v106
	v_pk_fma_f32 v[6:7], v[6:7], v[168:169], v[78:79] op_sel_hi:[1,0,1]
	v_add_f32_e32 v107, 1.0, v107
	v_rcp_f32_e32 v107, v107
	v_pk_fma_f32 v[16:17], v[16:17], v[168:169], v[84:85] op_sel_hi:[1,0,1]
	v_pk_fma_f32 v[2:3], v[2:3], v[168:169], v[70:71] op_sel_hi:[1,0,1]
	v_pk_fma_f32 v[8:9], v[8:9], v[168:169], v[80:81] op_sel_hi:[1,0,1]
	v_pk_mul_f32 v[106:107], v[128:129], v[106:107]
	v_pk_fma_f32 v[4:5], v[4:5], v[168:169], v[72:73] op_sel_hi:[1,0,1]
	v_pk_mul_f32 v[120:121], v[120:121], v[106:107]
	v_mul_f32_e32 v106, 0xbfb8aa3b, v125
	v_exp_f32_e32 v106, v106
	s_nop 0
	v_add_f32_e32 v106, 1.0, v106
	v_rcp_f32_e32 v127, v106
	s_nop 0
	v_pk_mul_f32 v[106:107], v[124:125], v[126:127]
	v_or_b32_e32 v126, 16, v166
	v_pk_mul_f32 v[124:125], v[108:109], v[106:107]
	v_cvt_pk_bf16_f32 v106, v118, v119
	v_mad_i64_i32 v[118:119], s[22:23], v126, s92, v[134:135]
	v_lshl_add_u64 v[118:119], v[118:119], 0, s[20:21]
	v_lshl_add_u64 v[118:119], v[118:119], 0, s[4:5]
	v_cvt_pk_bf16_f32 v107, v120, v121
	v_cvt_pk_bf16_f32 v108, v122, v123
	v_cvt_pk_bf16_f32 v109, v124, v125
	v_lshl_add_u64 v[118:119], v[118:119], 0, v[154:155]
	global_store_dwordx4 v[118:119], v[106:109], off nt
	s_nop 1
	v_pk_fma_f32 v[108:109], v[114:115], v[180:181], v[94:95] op_sel_hi:[1,0,1]
	v_mul_f32_e32 v115, 0xbfb8aa3b, v110
	v_exp_f32_e32 v115, v115
	v_pk_fma_f32 v[106:107], v[116:117], v[180:181], v[96:97] op_sel_hi:[1,0,1]
	v_mul_f32_e32 v114, 0xbfb8aa3b, v108
	v_exp_f32_e32 v114, v114
	v_add_f32_e32 v115, 1.0, v115
	v_rcp_f32_e32 v116, v115
	v_mul_f32_e32 v115, 0xbfb8aa3b, v109
	v_exp_f32_e32 v115, v115
	v_add_f32_e32 v114, 1.0, v114
	v_rcp_f32_e32 v114, v114
	v_add_f32_e32 v115, 1.0, v115
	v_rcp_f32_e32 v115, v115
	s_nop 0
	v_pk_mul_f32 v[108:109], v[108:109], v[114:115]
	s_nop 0
	v_pk_mul_f32 v[102:103], v[102:103], v[108:109]
	v_mul_f32_e32 v108, 0xbfb8aa3b, v111
	v_exp_f32_e32 v108, v108
	s_nop 0
	v_add_f32_e32 v108, 1.0, v108
	v_rcp_f32_e32 v117, v108
	s_nop 0
	v_pk_mul_f32 v[108:109], v[110:111], v[116:117]
	s_nop 0
	v_pk_mul_f32 v[108:109], v[86:87], v[108:109]
	v_mul_f32_e32 v87, 0xbfb8aa3b, v112
	v_exp_f32_e32 v87, v87
	v_mul_f32_e32 v86, 0xbfb8aa3b, v106
	v_exp_f32_e32 v86, v86
	v_add_f32_e32 v87, 1.0, v87
	v_rcp_f32_e32 v110, v87
	v_mul_f32_e32 v87, 0xbfb8aa3b, v107
	v_exp_f32_e32 v87, v87
	v_add_f32_e32 v86, 1.0, v86
	v_rcp_f32_e32 v86, v86
	v_add_f32_e32 v87, 1.0, v87
	v_rcp_f32_e32 v87, v87
	s_nop 0
	v_pk_mul_f32 v[86:87], v[106:107], v[86:87]
	s_nop 0
	v_pk_mul_f32 v[104:105], v[104:105], v[86:87]
	v_mul_f32_e32 v86, 0xbfb8aa3b, v113
	v_exp_f32_e32 v86, v86
	s_nop 0
	v_add_f32_e32 v86, 1.0, v86
	v_rcp_f32_e32 v111, v86
	s_nop 0
	v_pk_mul_f32 v[86:87], v[112:113], v[110:111]
	v_or_b32_e32 v110, 32, v166
	v_pk_mul_f32 v[106:107], v[88:89], v[86:87]
	v_cvt_pk_bf16_f32 v86, v102, v103
	v_mad_i64_i32 v[102:103], s[22:23], v110, s92, v[134:135]
	v_lshl_add_u64 v[102:103], v[102:103], 0, s[20:21]
	v_lshl_add_u64 v[102:103], v[102:103], 0, s[4:5]
	v_cvt_pk_bf16_f32 v87, v104, v105
	v_cvt_pk_bf16_f32 v88, v108, v109
	v_cvt_pk_bf16_f32 v89, v106, v107
	v_lshl_add_u64 v[102:103], v[102:103], 0, v[154:155]
	global_store_dwordx4 v[102:103], v[86:89], off nt
	s_nop 1
	v_pk_fma_f32 v[88:89], v[98:99], v[178:179], v[94:95] op_sel_hi:[1,0,1]
	v_mul_f32_e32 v99, 0xbfb8aa3b, v90
	v_exp_f32_e32 v99, v99
	v_pk_fma_f32 v[86:87], v[100:101], v[178:179], v[96:97] op_sel_hi:[1,0,1]
	v_mul_f32_e32 v98, 0xbfb8aa3b, v88
	v_exp_f32_e32 v98, v98
	v_add_f32_e32 v99, 1.0, v99
	v_rcp_f32_e32 v100, v99
	v_mul_f32_e32 v99, 0xbfb8aa3b, v89
	v_exp_f32_e32 v99, v99
	v_add_f32_e32 v98, 1.0, v98
	v_rcp_f32_e32 v98, v98
	v_add_f32_e32 v99, 1.0, v99
	v_rcp_f32_e32 v99, v99
	s_nop 0
	v_pk_mul_f32 v[88:89], v[88:89], v[98:99]
	s_nop 0
	v_pk_mul_f32 v[74:75], v[74:75], v[88:89]
	v_mul_f32_e32 v88, 0xbfb8aa3b, v91
	v_exp_f32_e32 v88, v88
	s_nop 0
	v_add_f32_e32 v88, 1.0, v88
	v_rcp_f32_e32 v101, v88
	s_nop 0
	v_pk_mul_f32 v[88:89], v[90:91], v[100:101]
	s_nop 0
	v_pk_mul_f32 v[88:89], v[66:67], v[88:89]
	v_mul_f32_e32 v67, 0xbfb8aa3b, v92
	v_exp_f32_e32 v67, v67
	v_mul_f32_e32 v66, 0xbfb8aa3b, v86
	v_exp_f32_e32 v66, v66
	v_add_f32_e32 v67, 1.0, v67
	v_rcp_f32_e32 v90, v67
	v_mul_f32_e32 v67, 0xbfb8aa3b, v87
	v_exp_f32_e32 v67, v67
	v_add_f32_e32 v66, 1.0, v66
	v_rcp_f32_e32 v66, v66
	v_add_f32_e32 v67, 1.0, v67
	v_rcp_f32_e32 v67, v67
	s_nop 0
	v_pk_mul_f32 v[66:67], v[86:87], v[66:67]
	s_nop 0
	v_pk_mul_f32 v[76:77], v[76:77], v[66:67]
	v_mul_f32_e32 v66, 0xbfb8aa3b, v93
	v_exp_f32_e32 v66, v66
	s_nop 0
	v_add_f32_e32 v66, 1.0, v66
	v_rcp_f32_e32 v91, v66
	s_nop 0
	v_pk_mul_f32 v[66:67], v[92:93], v[90:91]
	v_or_b32_e32 v90, 48, v166
	v_pk_mul_f32 v[86:87], v[68:69], v[66:67]
	v_cvt_pk_bf16_f32 v66, v74, v75
	v_mad_i64_i32 v[74:75], s[22:23], v90, s92, v[134:135]
	v_lshl_add_u64 v[74:75], v[74:75], 0, s[20:21]
	v_lshl_add_u64 v[74:75], v[74:75], 0, s[4:5]
	v_cvt_pk_bf16_f32 v67, v76, v77
	v_cvt_pk_bf16_f32 v68, v88, v89
	v_cvt_pk_bf16_f32 v69, v86, v87
	v_lshl_add_u64 v[74:75], v[74:75], 0, v[154:155]
	global_store_dwordx4 v[74:75], v[66:69], off nt
	s_nop 1
	v_mul_f32_e32 v67, 0xbfb8aa3b, v58
	v_exp_f32_e32 v67, v67
	v_mul_f32_e32 v66, 0xbfb8aa3b, v62
	v_exp_f32_e32 v66, v66
	v_add_f32_e32 v67, 1.0, v67
	v_rcp_f32_e32 v68, v67
	v_mul_f32_e32 v67, 0xbfb8aa3b, v63
	v_exp_f32_e32 v67, v67
	v_add_f32_e32 v66, 1.0, v66
	v_rcp_f32_e32 v66, v66
	v_add_f32_e32 v67, 1.0, v67
	v_rcp_f32_e32 v67, v67
	s_nop 0
	v_pk_mul_f32 v[62:63], v[62:63], v[66:67]
	s_nop 0
	v_pk_mul_f32 v[54:55], v[54:55], v[62:63]
	v_mul_f32_e32 v62, 0xbfb8aa3b, v59
	v_exp_f32_e32 v62, v62
	s_nop 0
	v_add_f32_e32 v62, 1.0, v62
	v_rcp_f32_e32 v69, v62
	s_nop 0
	v_pk_mul_f32 v[58:59], v[58:59], v[68:69]
	s_nop 0
	v_pk_mul_f32 v[58:59], v[42:43], v[58:59]
	v_mul_f32_e32 v43, 0xbfb8aa3b, v60
	v_exp_f32_e32 v43, v43
	v_mul_f32_e32 v42, 0xbfb8aa3b, v64
	v_exp_f32_e32 v42, v42
	v_add_f32_e32 v43, 1.0, v43
	v_rcp_f32_e32 v62, v43
	v_mul_f32_e32 v43, 0xbfb8aa3b, v65
	v_exp_f32_e32 v43, v43
	v_add_f32_e32 v42, 1.0, v42
	v_rcp_f32_e32 v42, v42
	v_add_f32_e32 v43, 1.0, v43
	v_rcp_f32_e32 v43, v43
	s_nop 0
	v_pk_mul_f32 v[42:43], v[64:65], v[42:43]
	s_nop 0
	v_pk_mul_f32 v[56:57], v[56:57], v[42:43]
	v_mul_f32_e32 v42, 0xbfb8aa3b, v61
	v_exp_f32_e32 v42, v42
	s_nop 0
	v_add_f32_e32 v42, 1.0, v42
	v_rcp_f32_e32 v63, v42
	s_nop 0
	v_pk_mul_f32 v[42:43], v[60:61], v[62:63]
	s_nop 0
	v_pk_mul_f32 v[60:61], v[44:45], v[42:43]
	v_cvt_pk_bf16_f32 v42, v54, v55
	v_mad_i64_i32 v[54:55], s[22:23], v174, s92, v[134:135]
	v_lshl_add_u64 v[54:55], v[54:55], 0, s[20:21]
	v_lshl_add_u64 v[54:55], v[54:55], 0, s[4:5]
	v_cvt_pk_bf16_f32 v43, v56, v57
	v_cvt_pk_bf16_f32 v44, v58, v59
	v_cvt_pk_bf16_f32 v45, v60, v61
	v_lshl_add_u64 v[54:55], v[54:55], 0, v[154:155]
	global_store_dwordx4 v[54:55], v[42:45], off nt
	s_nop 1
	v_pk_fma_f32 v[44:45], v[50:51], v[172:173], v[94:95] op_sel_hi:[1,0,1]
	v_mul_f32_e32 v51, 0xbfb8aa3b, v46
	v_exp_f32_e32 v51, v51
	v_pk_fma_f32 v[42:43], v[52:53], v[172:173], v[96:97] op_sel_hi:[1,0,1]
	v_mul_f32_e32 v50, 0xbfb8aa3b, v44
	v_exp_f32_e32 v50, v50
	v_add_f32_e32 v51, 1.0, v51
	v_rcp_f32_e32 v52, v51
	v_mul_f32_e32 v51, 0xbfb8aa3b, v45
	v_exp_f32_e32 v51, v51
	v_add_f32_e32 v50, 1.0, v50
	v_rcp_f32_e32 v50, v50
	v_add_f32_e32 v51, 1.0, v51
	v_rcp_f32_e32 v51, v51
	s_nop 0
	v_pk_mul_f32 v[44:45], v[44:45], v[50:51]
	s_nop 0
	v_pk_mul_f32 v[38:39], v[38:39], v[44:45]
	v_mul_f32_e32 v44, 0xbfb8aa3b, v47
	v_exp_f32_e32 v44, v44
	s_nop 0
	v_add_f32_e32 v44, 1.0, v44
	v_rcp_f32_e32 v53, v44
	s_nop 0
	v_pk_mul_f32 v[44:45], v[46:47], v[52:53]
	s_nop 0
	v_pk_mul_f32 v[44:45], v[26:27], v[44:45]
	v_mul_f32_e32 v27, 0xbfb8aa3b, v48
	v_exp_f32_e32 v27, v27
	v_mul_f32_e32 v26, 0xbfb8aa3b, v42
	v_exp_f32_e32 v26, v26
	v_add_f32_e32 v27, 1.0, v27
	v_rcp_f32_e32 v46, v27
	v_mul_f32_e32 v27, 0xbfb8aa3b, v43
	v_exp_f32_e32 v27, v27
	v_add_f32_e32 v26, 1.0, v26
	v_rcp_f32_e32 v26, v26
	v_add_f32_e32 v27, 1.0, v27
	v_rcp_f32_e32 v27, v27
	s_nop 0
	v_pk_mul_f32 v[26:27], v[42:43], v[26:27]
	s_nop 0
	v_pk_mul_f32 v[40:41], v[40:41], v[26:27]
	v_mul_f32_e32 v26, 0xbfb8aa3b, v49
	v_exp_f32_e32 v26, v26
	s_nop 0
	v_add_f32_e32 v26, 1.0, v26
	v_rcp_f32_e32 v47, v26
	s_nop 0
	v_pk_mul_f32 v[26:27], v[48:49], v[46:47]
	v_add_u32_e32 v46, 0x90, v166
	v_pk_mul_f32 v[42:43], v[28:29], v[26:27]
	v_cvt_pk_bf16_f32 v26, v38, v39
	v_mad_i64_i32 v[38:39], s[22:23], v46, s92, v[134:135]
	v_lshl_add_u64 v[38:39], v[38:39], 0, s[20:21]
	v_lshl_add_u64 v[38:39], v[38:39], 0, s[4:5]
	v_cvt_pk_bf16_f32 v27, v40, v41
	v_cvt_pk_bf16_f32 v28, v44, v45
	v_cvt_pk_bf16_f32 v29, v42, v43
	v_lshl_add_u64 v[38:39], v[38:39], 0, v[154:155]
	global_store_dwordx4 v[38:39], v[26:29], off nt
	s_nop 1
	v_pk_fma_f32 v[28:29], v[34:35], v[170:171], v[94:95] op_sel_hi:[1,0,1]
	v_mul_f32_e32 v35, 0xbfb8aa3b, v30
	v_exp_f32_e32 v35, v35
	v_pk_fma_f32 v[26:27], v[36:37], v[170:171], v[96:97] op_sel_hi:[1,0,1]
	v_mul_f32_e32 v34, 0xbfb8aa3b, v28
	v_exp_f32_e32 v34, v34
	v_add_f32_e32 v35, 1.0, v35
	v_rcp_f32_e32 v36, v35
	v_mul_f32_e32 v35, 0xbfb8aa3b, v29
	v_exp_f32_e32 v35, v35
	v_add_f32_e32 v34, 1.0, v34
	v_rcp_f32_e32 v34, v34
	v_add_f32_e32 v35, 1.0, v35
	v_rcp_f32_e32 v35, v35
	s_nop 0
	v_pk_mul_f32 v[28:29], v[28:29], v[34:35]
	s_nop 0
	v_pk_mul_f32 v[22:23], v[22:23], v[28:29]
	v_mul_f32_e32 v28, 0xbfb8aa3b, v31
	v_exp_f32_e32 v28, v28
	s_nop 0
	v_add_f32_e32 v28, 1.0, v28
	v_rcp_f32_e32 v37, v28
	s_nop 0
	v_pk_mul_f32 v[28:29], v[30:31], v[36:37]
	s_nop 0
	v_pk_mul_f32 v[28:29], v[10:11], v[28:29]
	v_mul_f32_e32 v11, 0xbfb8aa3b, v32
	v_exp_f32_e32 v11, v11
	v_mul_f32_e32 v10, 0xbfb8aa3b, v26
	v_exp_f32_e32 v10, v10
	v_add_f32_e32 v11, 1.0, v11
	v_rcp_f32_e32 v30, v11
	v_mul_f32_e32 v11, 0xbfb8aa3b, v27
	v_exp_f32_e32 v11, v11
	v_add_f32_e32 v10, 1.0, v10
	v_rcp_f32_e32 v10, v10
	v_add_f32_e32 v11, 1.0, v11
	v_rcp_f32_e32 v11, v11
	s_nop 0
	v_pk_mul_f32 v[10:11], v[26:27], v[10:11]
	s_nop 0
	v_pk_mul_f32 v[24:25], v[24:25], v[10:11]
	v_mul_f32_e32 v10, 0xbfb8aa3b, v33
	v_exp_f32_e32 v10, v10
	s_nop 0
	v_add_f32_e32 v10, 1.0, v10
	v_rcp_f32_e32 v31, v10
	s_nop 0
	v_pk_mul_f32 v[10:11], v[32:33], v[30:31]
	v_add_u32_e32 v30, 0xa0, v166
	v_pk_mul_f32 v[26:27], v[12:13], v[10:11]
	v_cvt_pk_bf16_f32 v10, v22, v23
	v_mad_i64_i32 v[22:23], s[22:23], v30, s92, v[134:135]
	v_lshl_add_u64 v[22:23], v[22:23], 0, s[20:21]
	v_lshl_add_u64 v[22:23], v[22:23], 0, s[4:5]
	v_cvt_pk_bf16_f32 v11, v24, v25
	v_cvt_pk_bf16_f32 v12, v28, v29
	v_cvt_pk_bf16_f32 v13, v26, v27
	v_lshl_add_u64 v[22:23], v[22:23], 0, v[154:155]
	global_store_dwordx4 v[22:23], v[10:13], off nt
	s_nop 1
	v_pk_fma_f32 v[12:13], v[18:19], v[168:169], v[94:95] op_sel_hi:[1,0,1]
	v_mul_f32_e32 v19, 0xbfb8aa3b, v14
	v_exp_f32_e32 v19, v19
	v_pk_fma_f32 v[10:11], v[20:21], v[168:169], v[96:97] op_sel_hi:[1,0,1]
	v_mul_f32_e32 v18, 0xbfb8aa3b, v12
	v_exp_f32_e32 v18, v18
	v_add_f32_e32 v19, 1.0, v19
	v_rcp_f32_e32 v20, v19
	v_mul_f32_e32 v19, 0xbfb8aa3b, v13
	v_exp_f32_e32 v19, v19
	v_add_f32_e32 v18, 1.0, v18
	v_rcp_f32_e32 v18, v18
	v_add_f32_e32 v19, 1.0, v19
	v_rcp_f32_e32 v19, v19
	s_nop 0
	v_pk_mul_f32 v[12:13], v[12:13], v[18:19]
	s_nop 0
	v_pk_mul_f32 v[6:7], v[6:7], v[12:13]
	v_mul_f32_e32 v12, 0xbfb8aa3b, v15
	v_exp_f32_e32 v12, v12
	s_nop 0
	v_add_f32_e32 v12, 1.0, v12
	v_rcp_f32_e32 v21, v12
	s_nop 0
	v_pk_mul_f32 v[12:13], v[14:15], v[20:21]
	s_nop 0
	v_pk_mul_f32 v[12:13], v[2:3], v[12:13]
	v_mul_f32_e32 v3, 0xbfb8aa3b, v16
	v_exp_f32_e32 v3, v3
	v_mul_f32_e32 v2, 0xbfb8aa3b, v10
	v_exp_f32_e32 v2, v2
	v_add_f32_e32 v3, 1.0, v3
	v_rcp_f32_e32 v14, v3
	v_mul_f32_e32 v3, 0xbfb8aa3b, v11
	v_exp_f32_e32 v3, v3
	v_add_f32_e32 v2, 1.0, v2
	v_rcp_f32_e32 v2, v2
	v_add_f32_e32 v3, 1.0, v3
	v_rcp_f32_e32 v3, v3
	s_nop 0
	v_pk_mul_f32 v[2:3], v[10:11], v[2:3]
	s_nop 0
	v_pk_mul_f32 v[8:9], v[8:9], v[2:3]
	v_mul_f32_e32 v2, 0xbfb8aa3b, v17
	v_exp_f32_e32 v2, v2
	s_nop 0
	v_add_f32_e32 v2, 1.0, v2
	v_rcp_f32_e32 v15, v2
	s_nop 0
	v_pk_mul_f32 v[2:3], v[16:17], v[14:15]
	v_add_u32_e32 v14, 0xb0, v166
	v_pk_mul_f32 v[10:11], v[4:5], v[2:3]
	v_cvt_pk_bf16_f32 v2, v6, v7
	v_mad_i64_i32 v[6:7], s[22:23], v14, s92, v[134:135]
	v_lshl_add_u64 v[6:7], v[6:7], 0, s[20:21]
	v_lshl_add_u64 v[6:7], v[6:7], 0, s[4:5]
	v_cvt_pk_bf16_f32 v3, v8, v9
	v_cvt_pk_bf16_f32 v4, v12, v13
	v_cvt_pk_bf16_f32 v5, v10, v11
	v_lshl_add_u64 v[6:7], v[6:7], 0, v[154:155]
	s_mov_b64 s[20:21], -1
	global_store_dwordx4 v[6:7], v[2:5], off nt
	s_cbranch_vccnz .LBB0_1290
	s_andn2_b64 vcc, exec, s[6:7]
	s_cbranch_vccnz .LBB0_1289
	s_barrier
	s_branch .LBB0_1289
